# short-conv items rebalanced by workgroup class: vcu>=128 items 0..1279 stride 1024, 64..127 items 1280..3327 stride 512, vcu<64 items 3328..4351 stride 512 (an item costs a wave ~8 us)
# speedup vs baseline: 1.0038x; 1.0038x over previous
; __global__ void __launch_bounds__(512, 2) mk_fwd(Args args) {
;     ...
;             if (G == 256) {
;                 if (vcu >= 128) attn_sample_unit(args, l, vcu - 128, lds, tid);
;     ...
;                 if (vcu >= 64) for (int it = (vcu - 64) * 8 + wave; it < (MT / 8) * 2; it += 192 * 8) sconv_item(args, l, it, lane);
;     ...
;             } else {
;                 for (int u = vcu; u < 128; u += G) attn_sample_unit(args, l, u, lds, tid);
;     ...
;                 for (int it = gw; it < (MT / 8) * 2; it += ngw) sconv_item(args, l, it, lane);
.LBB0_658:
	v_readlane_b32 s0, v253, 52
	v_readlane_b32 s1, v253, 53
	s_andn2_b64 vcc, exec, s[0:1]
	v_readlane_b32 s2, v254, 49
	v_readlane_b32 s3, v254, 42
	v_readlane_b32 s14, v254, 47
	v_readlane_b32 s4, v249, 2
	s_nop 1
	s_cmp_lt_u32 s4, 0x80
	s_cbranch_scc1 .Lrb_notB
	s_add_i32 s14, s14, -512
	s_add_i32 s2, s2, -2048
	s_add_i32 s3, s3, -262144
	s_movk_i32 s5, 0x400
	s_mov_b32 s6, -257
	s_branch .Lrb_set
.Lrb_notB:
	s_cmp_lt_u32 s4, 0x40
	s_cbranch_scc1 .Lrb_c0
	s_add_i32 s14, s14, 1280
	s_add_i32 s2, s2, 5120
	s_add_i32 s3, s3, 655360
	s_movk_i32 s5, 0x200
	s_mov_b32 s6, 1791
	s_branch .Lrb_set
.Lrb_c0:
	s_add_i32 s14, s14, 3840
	s_add_i32 s2, s2, 15360
	s_add_i32 s3, s3, 1966080
	s_movk_i32 s5, 0x200
	s_mov_b32 s6, 2815
.Lrb_set:
	v_writelane_b32 v255, s5, 44
	v_writelane_b32 v255, s6, 45
	s_branch .LBB0_686
